# attention loops: back-edge rotated (exit test and loop-carried copy before the loop-back barrier; GQA barrier is the loop head)
# baseline (speedup 1.0000x reference)
; #define SBAR() __builtin_amdgcn_sched_barrier(0)
; #define SWAIT() do { if constexpr (SD == 1) asm volatile("s_waitcnt vmcnt(0)" ::: "memory"); else asm volatile("s_waitcnt vmcnt(4)" ::: "memory"); } while (0)
; #define RESC(a) do { if (__any((a) < 1.f)) { if (hi == 0) al_l[r32] = (a); asm volatile("s_waitcnt lgkmcnt(0)" ::: "memory"); \
;     _Pragma("unroll") for (int d = 0; d < 4; ++d) _Pragma("unroll") for (int r = 0; r < 16; ++r) o[d][r] *= al_l[crow(r, hi)]; } } while (0)
; __device__ __forceinline__ void finishSM(f32x16& p0, f32x16& p1, float alpha, float& l_reg, bf16x8& pa0, bf16x8& pa1, bf16x8& pa2, bf16x8& pa3) {
;     ...
;   l_reg = l_reg * alpha + ps;
; template <int DQK, int LDK> ...
;     ...
;   for (int j = 1; j + 1 < NT; j += 2) {
;     SBAR(); qkt<DQK>(pB0, pB1, (bf16_t*)((char*)K_lds + SHM_K), KR_lds + SHM_KR, QRw, qr, r32, hi);
;     finishSM(pA0, pA1, alA, l_reg, pa0, pa1, pa2, pa3); SBAR();
;     SLOAD(SO, (j + SD) * KVBLK); SBAR();
;     pv_partialSM<DQK>(o, vb0, pa0, pa1, pa2, pa3, pB0, pB1, m_reg, alB);
;     __syncthreads(); SWAIT(); SWRITE(0, SE);
;     RESC(alB); __syncthreads();
;     SBAR(); qkt<DQK>(pA0, pA1, K_lds, KR_lds, QRw, qr, r32, hi);
;     finishSM(pB0, pB1, alB, l_reg, pa0, pa1, pa2, pa3); SBAR();
;     if (SD == 1 || j + 3 < NT) SLOAD(SE, (j + 1 + SD) * KVBLK); SBAR();
;     pv_partialSM<DQK>(o, vb0 + (int)SHM_V, pa0, pa1, pa2, pa3, pA0, pA1, m_reg, alA);
;     __syncthreads(); SWAIT(); SWRITE(1, SO);
;     RESC(alA); __syncthreads();
.LBB0_351:
	v_add_f32_e32 v98, v230, v231
	s_mov_b64 s[2:3], 0x4000
	v_fmac_f32_e32 v98, v220, v180
	v_add_f32_e32 v180, v234, v235
	v_lshl_add_u64 v[168:169], v[168:169], 0, s[2:3]
	s_add_i32 s16, s16, 2
	s_mov_b64 s[2:3], 0x80000
	v_fmac_f32_e32 v180, v98, v232
	s_cmp_ge_u32 s16, s15
	v_lshl_add_u64 v[170:171], v[170:171], 0, s[2:3]
	s_waitcnt lgkmcnt(0)
	s_cbranch_scc1 .Lmla_exit
	v_mov_b32_e32 v220, v172
	s_barrier
	s_branch .LBB0_343
.Lmla_exit:
	s_barrier

; #define SBAR() __builtin_amdgcn_sched_barrier(0)
; #define SWAIT() do { if constexpr (SD == 1) asm volatile("s_waitcnt vmcnt(0)" ::: "memory"); else asm volatile("s_waitcnt vmcnt(4)" ::: "memory"); } while (0)
; #define RESC(a) do { if (__any((a) < 1.f)) { if (hi == 0) al_l[r32] = (a); asm volatile("s_waitcnt lgkmcnt(0)" ::: "memory"); \
;     _Pragma("unroll") for (int d = 0; d < 4; ++d) _Pragma("unroll") for (int r = 0; r < 16; ++r) o[d][r] *= al_l[crow(r, hi)]; } } while (0)
; template <int DQK, int LDK> ...
;     ...
;   for (int j = 1; j + 1 < NT; j += 2) {
;     SBAR(); qkt<DQK>(pB0, pB1, (bf16_t*)((char*)K_lds + SHM_K), KR_lds + SHM_KR, QRw, qr, r32, hi);
;     finishSM(pA0, pA1, alA, l_reg, pa0, pa1, pa2, pa3); SBAR();
;     SLOAD(SO, (j + SD) * KVBLK); SBAR();
;     pv_partialSM<DQK>(o, vb0, pa0, pa1, pa2, pa3, pB0, pB1, m_reg, alB);
;     __syncthreads(); SWAIT(); SWRITE(0, SE);
;     RESC(alB); __syncthreads();
;     SBAR(); qkt<DQK>(pA0, pA1, K_lds, KR_lds, QRw, qr, r32, hi);
;     finishSM(pB0, pB1, alB, l_reg, pa0, pa1, pa2, pa3); SBAR();
;     if (SD == 1 || j + 3 < NT) SLOAD(SE, (j + 1 + SD) * KVBLK); SBAR();
;     pv_partialSM<DQK>(o, vb0 + (int)SHM_V, pa0, pa1, pa2, pa3, pA0, pA1, m_reg, alA);
;     __syncthreads(); SWAIT(); SWRITE(1, SO);
;     RESC(alA); __syncthreads();
.LBB0_488:
	v_add_f32_e32 v98, v224, v225
	v_fmac_f32_e32 v98, v222, v215
	v_add_f32_e32 v215, v114, v115
	v_fmac_f32_e32 v215, v98, v227
	s_add_i32 s16, s16, 2
	v_lshl_add_u64 v[198:199], v[198:199], 0, s[24:25]
	s_and_b64 vcc, exec, s[2:3]
	s_waitcnt lgkmcnt(0)
	s_cbranch_vccnz .Lgqa_exit
	v_mov_b32_e32 v222, v223
	s_branch .Lgqa_head
